# v28 with GU steady loop shifted by 4 bytes (alignment test)
# speedup vs baseline: 1.0079x; 1.0079x over previous
.LBB0_531:
	s_add_u32 s8, s8, 0x80180
	s_addc_u32 s9, s9, 0
	s_add_u32 s26, s6, 0x200
	s_addc_u32 s27, s7, 0
	s_mov_b32 s28, 0
	v_mov_b32_e32 v2, v138
	s_nop 0
.LBB0_532:
	s_add_u32 s6, s8, 0xfff80080
	s_addc_u32 s7, s9, -1
	s_add_i32 s29, 0, 0x10000
	s_cmp_eq_u32 s28, 28
	s_cselect_b32 s17, s13, s7
	s_cselect_b32 s16, s12, s6
	v_add_u32_e32 v133, s29, v147
	s_cselect_b32 s7, s15, s27
	s_cselect_b32 s6, s14, s26
	s_add_i32 s53, 0, 0x14000
	ds_read_b128 v[138:141], v133
	ds_read_b128 v[142:145], v133 offset:1024
	ds_read_b128 v[148:151], v133 offset:2048
	ds_read_b128 v[152:155], v133 offset:3072
	v_add_u32_e32 v133, s53, v147
	ds_read_b128 v[156:159], v133
	ds_read_b128 v[160:163], v133 offset:1024
	ds_read_b128 v[164:167], v133 offset:2048
	ds_read_b128 v[168:171], v133 offset:3072
	s_mov_b32 m0, s66
	v_add_u32_e32 v212, 0, v146
	ds_read_b128 v[172:175], v212
	ds_read_b128 v[176:179], v212 offset:1024
	ds_read_b128 v[180:183], v212 offset:2048
	ds_read_b128 v[184:187], v212 offset:3072
	ds_read_b128 v[188:191], v212 offset:4096
	ds_read_b128 v[192:195], v212 offset:5120
	ds_read_b128 v[196:199], v212 offset:6144
	ds_read_b128 v[200:203], v212 offset:7168
	global_load_lds_dwordx4 v2, s[8:9]
	s_mov_b32 m0, s67
	v_mov_b32_e32 v133, v3
	global_load_lds_dwordx4 v132, s[8:9]
	s_waitcnt vmcnt(8)
	s_waitcnt lgkmcnt(0)
	s_barrier
	s_setprio 1
	s_waitcnt lgkmcnt(0)
	v_mfma_f32_16x16x32_f16 v[4:7], v[138:141], v[172:175], v[4:7]
	v_mfma_f32_16x16x32_f16 v[4:7], v[142:145], v[176:179], v[4:7]
	v_mfma_f32_16x16x32_f16 v[8:11], v[152:155], v[176:179], v[8:11]
	v_mfma_f32_16x16x32_f16 v[8:11], v[148:151], v[172:175], v[8:11]
	v_mfma_f32_16x16x32_f16 v[16:19], v[148:151], v[180:183], v[16:19]
	v_mfma_f32_16x16x32_f16 v[16:19], v[152:155], v[184:187], v[16:19]
	v_mfma_f32_16x16x32_f16 v[12:15], v[142:145], v[184:187], v[12:15]
	v_mfma_f32_16x16x32_f16 v[12:15], v[138:141], v[180:183], v[12:15]
	v_mfma_f32_16x16x32_f16 v[20:23], v[138:141], v[188:191], v[20:23]
	v_mfma_f32_16x16x32_f16 v[20:23], v[142:145], v[192:195], v[20:23]
	v_mfma_f32_16x16x32_f16 v[24:27], v[152:155], v[192:195], v[24:27]
	v_mfma_f32_16x16x32_f16 v[24:27], v[148:151], v[188:191], v[24:27]
	v_mfma_f32_16x16x32_f16 v[32:35], v[148:151], v[196:199], v[32:35]
	v_mfma_f32_16x16x32_f16 v[32:35], v[152:155], v[200:203], v[32:35]
	v_mfma_f32_16x16x32_f16 v[28:31], v[142:145], v[200:203], v[28:31]
	v_mfma_f32_16x16x32_f16 v[28:31], v[138:141], v[196:199], v[28:31]
	s_setprio 0
	s_setprio 1
	v_mfma_f32_16x16x32_f16 v[36:39], v[156:159], v[172:175], v[36:39]
	v_mfma_f32_16x16x32_f16 v[36:39], v[160:163], v[176:179], v[36:39]
	v_mfma_f32_16x16x32_f16 v[40:43], v[168:171], v[176:179], v[40:43]
	v_mfma_f32_16x16x32_f16 v[40:43], v[164:167], v[172:175], v[40:43]
	v_mfma_f32_16x16x32_f16 v[48:51], v[164:167], v[180:183], v[48:51]
	v_mfma_f32_16x16x32_f16 v[48:51], v[168:171], v[184:187], v[48:51]
	v_mfma_f32_16x16x32_f16 v[44:47], v[160:163], v[184:187], v[44:47]
	v_mfma_f32_16x16x32_f16 v[44:47], v[156:159], v[180:183], v[44:47]
	v_mfma_f32_16x16x32_f16 v[52:55], v[156:159], v[188:191], v[52:55]
	v_mfma_f32_16x16x32_f16 v[52:55], v[160:163], v[192:195], v[52:55]
	v_mfma_f32_16x16x32_f16 v[56:59], v[168:171], v[192:195], v[56:59]
	v_mfma_f32_16x16x32_f16 v[56:59], v[164:167], v[188:191], v[56:59]
	v_mfma_f32_16x16x32_f16 v[64:67], v[164:167], v[196:199], v[64:67]
	v_mfma_f32_16x16x32_f16 v[64:67], v[168:171], v[200:203], v[64:67]
	s_setprio 2
	s_barrier
	v_mfma_f32_16x16x32_f16 v[60:63], v[160:163], v[200:203], v[60:63]
	v_mfma_f32_16x16x32_f16 v[60:63], v[156:159], v[196:199], v[60:63]
	s_setprio 0
	s_add_i32 s29, s29, s38
	s_mov_b32 m0, s29
	ds_read_b128 v[172:175], v212 offset:16384
	ds_read_b128 v[176:179], v212 offset:17408
	ds_read_b128 v[180:183], v212 offset:18432
	ds_read_b128 v[184:187], v212 offset:19456
	ds_read_b128 v[188:191], v212 offset:20480
	ds_read_b128 v[192:195], v212 offset:21504
	ds_read_b128 v[196:199], v212 offset:22528
	ds_read_b128 v[200:203], v212 offset:23552
	global_load_lds_dwordx4 v136, s[6:7]
	s_add_i32 m0, s29, 0x2000
	s_add_u32 s40, s6, 0x80000
	s_addc_u32 s41, s7, 0
	s_add_i32 s29, s53, s38
	global_load_lds_dwordx4 v134, s[6:7]
	s_mov_b32 m0, s29
	v_mov_b32_e32 v137, v3
	global_load_lds_dwordx4 v136, s[40:41]
	s_add_i32 m0, s29, 0x2000
	v_mov_b32_e32 v135, v3
	global_load_lds_dwordx4 v134, s[40:41]
	s_mov_b32 m0, s58
	v_lshl_add_u64 v[204:205], s[6:7], 0, v[136:137]
	global_load_lds_dwordx4 v2, s[16:17]
	s_mov_b32 m0, s59
	v_lshl_add_u64 v[206:207], s[6:7], 0, v[134:135]
	global_load_lds_dwordx4 v132, s[16:17]
	s_waitcnt vmcnt(8)
	s_waitcnt lgkmcnt(0)
	v_lshl_add_u64 v[208:209], s[16:17], 0, v[2:3]
	v_lshl_add_u64 v[210:211], s[16:17], 0, v[132:133]
	s_barrier
	s_setprio 1
	s_waitcnt lgkmcnt(0)
	v_mfma_f32_16x16x32_f16 v[68:71], v[138:141], v[172:175], v[68:71]
	v_mfma_f32_16x16x32_f16 v[68:71], v[142:145], v[176:179], v[68:71]
	v_mfma_f32_16x16x32_f16 v[72:75], v[152:155], v[176:179], v[72:75]
	v_mfma_f32_16x16x32_f16 v[72:75], v[148:151], v[172:175], v[72:75]
	v_mfma_f32_16x16x32_f16 v[80:83], v[148:151], v[180:183], v[80:83]
	v_mfma_f32_16x16x32_f16 v[80:83], v[152:155], v[184:187], v[80:83]
	v_mfma_f32_16x16x32_f16 v[76:79], v[142:145], v[184:187], v[76:79]
	v_mfma_f32_16x16x32_f16 v[76:79], v[138:141], v[180:183], v[76:79]
	v_mfma_f32_16x16x32_f16 v[84:87], v[138:141], v[188:191], v[84:87]
	v_mfma_f32_16x16x32_f16 v[84:87], v[142:145], v[192:195], v[84:87]
	v_mfma_f32_16x16x32_f16 v[88:91], v[152:155], v[192:195], v[88:91]
	v_mfma_f32_16x16x32_f16 v[88:91], v[148:151], v[188:191], v[88:91]
	v_mfma_f32_16x16x32_f16 v[96:99], v[148:151], v[196:199], v[96:99]
	v_mfma_f32_16x16x32_f16 v[96:99], v[152:155], v[200:203], v[96:99]
	v_mfma_f32_16x16x32_f16 v[92:95], v[142:145], v[200:203], v[92:95]
	v_mfma_f32_16x16x32_f16 v[92:95], v[138:141], v[196:199], v[92:95]
	s_setprio 0
	s_setprio 1
	v_mfma_f32_16x16x32_f16 v[100:103], v[156:159], v[172:175], v[100:103]
	v_mfma_f32_16x16x32_f16 v[100:103], v[160:163], v[176:179], v[100:103]
	v_mfma_f32_16x16x32_f16 v[104:107], v[168:171], v[176:179], v[104:107]
	v_mfma_f32_16x16x32_f16 v[104:107], v[164:167], v[172:175], v[104:107]
	v_mfma_f32_16x16x32_f16 v[112:115], v[164:167], v[180:183], v[112:115]
	v_mfma_f32_16x16x32_f16 v[112:115], v[168:171], v[184:187], v[112:115]
	v_mfma_f32_16x16x32_f16 v[108:111], v[160:163], v[184:187], v[108:111]
	v_mfma_f32_16x16x32_f16 v[108:111], v[156:159], v[180:183], v[108:111]
	v_mfma_f32_16x16x32_f16 v[116:119], v[156:159], v[188:191], v[116:119]
	v_mfma_f32_16x16x32_f16 v[116:119], v[160:163], v[192:195], v[116:119]
	v_mfma_f32_16x16x32_f16 v[120:123], v[168:171], v[192:195], v[120:123]
	v_mfma_f32_16x16x32_f16 v[120:123], v[164:167], v[188:191], v[120:123]
	v_mfma_f32_16x16x32_f16 v[128:131], v[164:167], v[196:199], v[128:131]
	v_mfma_f32_16x16x32_f16 v[128:131], v[168:171], v[200:203], v[128:131]
	s_setprio 2
	s_barrier
	v_mfma_f32_16x16x32_f16 v[124:127], v[160:163], v[200:203], v[124:127]
	v_mfma_f32_16x16x32_f16 v[124:127], v[156:159], v[196:199], v[124:127]
	s_setprio 0
	s_add_i32 s29, 0, 0x18000
	v_add_u32_e32 v135, s29, v147
	s_add_i32 s40, 0, 0x1c000
	ds_read_b128 v[138:141], v135
	ds_read_b128 v[142:145], v135 offset:1024
	ds_read_b128 v[148:151], v135 offset:2048
	ds_read_b128 v[152:155], v135 offset:3072
	v_add_u32_e32 v135, s40, v147
	ds_read_b128 v[156:159], v135
	ds_read_b128 v[160:163], v135 offset:1024
	ds_read_b128 v[164:167], v135 offset:2048
	ds_read_b128 v[168:171], v135 offset:3072
	s_add_u32 s16, s16, 0x80000
	s_addc_u32 s17, s17, 0
	s_mov_b32 m0, s60
	ds_read_b128 v[172:175], v212 offset:32768
	ds_read_b128 v[176:179], v212 offset:33792
	ds_read_b128 v[180:183], v212 offset:34816
	ds_read_b128 v[184:187], v212 offset:35840
	ds_read_b128 v[188:191], v212 offset:36864
	ds_read_b128 v[192:195], v212 offset:37888
	ds_read_b128 v[196:199], v212 offset:38912
	ds_read_b128 v[200:203], v212 offset:39936
	global_load_lds_dwordx4 v2, s[16:17]
	s_mov_b32 m0, s61
	s_nop 0
	global_load_lds_dwordx4 v132, s[16:17]
	s_waitcnt vmcnt(8)
	s_waitcnt lgkmcnt(0)
	s_barrier
	s_setprio 1
	s_waitcnt lgkmcnt(0)
	v_mfma_f32_16x16x32_f16 v[4:7], v[138:141], v[172:175], v[4:7]
	v_mfma_f32_16x16x32_f16 v[4:7], v[142:145], v[176:179], v[4:7]
	v_mfma_f32_16x16x32_f16 v[8:11], v[152:155], v[176:179], v[8:11]
	v_mfma_f32_16x16x32_f16 v[8:11], v[148:151], v[172:175], v[8:11]
	v_mfma_f32_16x16x32_f16 v[16:19], v[148:151], v[180:183], v[16:19]
	v_mfma_f32_16x16x32_f16 v[16:19], v[152:155], v[184:187], v[16:19]
	v_mfma_f32_16x16x32_f16 v[12:15], v[142:145], v[184:187], v[12:15]
	v_mfma_f32_16x16x32_f16 v[12:15], v[138:141], v[180:183], v[12:15]
	v_mfma_f32_16x16x32_f16 v[20:23], v[138:141], v[188:191], v[20:23]
	v_mfma_f32_16x16x32_f16 v[20:23], v[142:145], v[192:195], v[20:23]
	v_mfma_f32_16x16x32_f16 v[24:27], v[152:155], v[192:195], v[24:27]
	v_mfma_f32_16x16x32_f16 v[24:27], v[148:151], v[188:191], v[24:27]
	v_mfma_f32_16x16x32_f16 v[32:35], v[148:151], v[196:199], v[32:35]
	v_mfma_f32_16x16x32_f16 v[32:35], v[152:155], v[200:203], v[32:35]
	v_mfma_f32_16x16x32_f16 v[28:31], v[142:145], v[200:203], v[28:31]
	v_mfma_f32_16x16x32_f16 v[28:31], v[138:141], v[196:199], v[28:31]
	s_setprio 0
	s_setprio 1
	v_mfma_f32_16x16x32_f16 v[36:39], v[156:159], v[172:175], v[36:39]
	v_mfma_f32_16x16x32_f16 v[36:39], v[160:163], v[176:179], v[36:39]
	v_mfma_f32_16x16x32_f16 v[40:43], v[168:171], v[176:179], v[40:43]
	v_mfma_f32_16x16x32_f16 v[40:43], v[164:167], v[172:175], v[40:43]
	v_mfma_f32_16x16x32_f16 v[48:51], v[164:167], v[180:183], v[48:51]
	v_mfma_f32_16x16x32_f16 v[48:51], v[168:171], v[184:187], v[48:51]
	v_mfma_f32_16x16x32_f16 v[44:47], v[160:163], v[184:187], v[44:47]
	v_mfma_f32_16x16x32_f16 v[44:47], v[156:159], v[180:183], v[44:47]
	v_mfma_f32_16x16x32_f16 v[52:55], v[156:159], v[188:191], v[52:55]
	v_mfma_f32_16x16x32_f16 v[52:55], v[160:163], v[192:195], v[52:55]
	v_mfma_f32_16x16x32_f16 v[56:59], v[168:171], v[192:195], v[56:59]
	v_mfma_f32_16x16x32_f16 v[56:59], v[164:167], v[188:191], v[56:59]
	v_mfma_f32_16x16x32_f16 v[64:67], v[164:167], v[196:199], v[64:67]
	v_mfma_f32_16x16x32_f16 v[64:67], v[168:171], v[200:203], v[64:67]
	s_setprio 2
	s_barrier
	v_mfma_f32_16x16x32_f16 v[60:63], v[160:163], v[200:203], v[60:63]
	v_mfma_f32_16x16x32_f16 v[60:63], v[156:159], v[196:199], v[60:63]
	s_setprio 0
	s_add_i32 s16, s29, s38
	v_lshl_add_u64 v[204:205], v[204:205], 0, s[86:87]
	s_mov_b32 m0, s16
	ds_read_b128 v[172:175], v212 offset:49152
	ds_read_b128 v[176:179], v212 offset:50176
	ds_read_b128 v[180:183], v212 offset:51200
	ds_read_b128 v[184:187], v212 offset:52224
	ds_read_b128 v[188:191], v212 offset:53248
	ds_read_b128 v[192:195], v212 offset:54272
	ds_read_b128 v[196:199], v212 offset:55296
	ds_read_b128 v[200:203], v212 offset:56320
	global_load_lds_dwordx4 v[204:205], off
	s_add_i32 m0, s16, 0x2000
	s_add_u32 s6, s6, 0x80080
	v_lshl_add_u64 v[204:205], v[206:207], 0, s[86:87]
	s_addc_u32 s7, s7, 0
	s_add_i32 s16, s40, s38
	global_load_lds_dwordx4 v[204:205], off
	s_mov_b32 m0, s16
	v_lshl_add_u64 v[204:205], v[208:209], 0, s[86:87]
	global_load_lds_dwordx4 v136, s[6:7]
	s_add_i32 m0, s16, 0x2000
	s_nop 0
	global_load_lds_dwordx4 v134, s[6:7]
	s_mov_b32 m0, s64
	s_nop 0
	global_load_lds_dwordx4 v[204:205], off
	v_lshl_add_u64 v[204:205], v[210:211], 0, s[86:87]
	s_mov_b32 m0, s65
	s_nop 0
	global_load_lds_dwordx4 v[204:205], off
	s_waitcnt vmcnt(8)
	s_waitcnt lgkmcnt(0)
	s_barrier
	s_setprio 1
	s_waitcnt lgkmcnt(0)
	v_mfma_f32_16x16x32_f16 v[68:71], v[138:141], v[172:175], v[68:71]
	v_mfma_f32_16x16x32_f16 v[68:71], v[142:145], v[176:179], v[68:71]
	v_mfma_f32_16x16x32_f16 v[72:75], v[152:155], v[176:179], v[72:75]
	v_mfma_f32_16x16x32_f16 v[72:75], v[148:151], v[172:175], v[72:75]
	v_mfma_f32_16x16x32_f16 v[80:83], v[148:151], v[180:183], v[80:83]
	v_mfma_f32_16x16x32_f16 v[80:83], v[152:155], v[184:187], v[80:83]
	v_mfma_f32_16x16x32_f16 v[76:79], v[142:145], v[184:187], v[76:79]
	v_mfma_f32_16x16x32_f16 v[76:79], v[138:141], v[180:183], v[76:79]
	v_mfma_f32_16x16x32_f16 v[84:87], v[138:141], v[188:191], v[84:87]
	v_mfma_f32_16x16x32_f16 v[84:87], v[142:145], v[192:195], v[84:87]
	v_mfma_f32_16x16x32_f16 v[88:91], v[152:155], v[192:195], v[88:91]
	v_mfma_f32_16x16x32_f16 v[88:91], v[148:151], v[188:191], v[88:91]
	v_mfma_f32_16x16x32_f16 v[96:99], v[148:151], v[196:199], v[96:99]
	v_mfma_f32_16x16x32_f16 v[96:99], v[152:155], v[200:203], v[96:99]
	v_mfma_f32_16x16x32_f16 v[92:95], v[142:145], v[200:203], v[92:95]
	v_mfma_f32_16x16x32_f16 v[92:95], v[138:141], v[196:199], v[92:95]
	s_setprio 0
	s_setprio 1
	v_mfma_f32_16x16x32_f16 v[100:103], v[156:159], v[172:175], v[100:103]
	v_mfma_f32_16x16x32_f16 v[100:103], v[160:163], v[176:179], v[100:103]
	v_mfma_f32_16x16x32_f16 v[104:107], v[168:171], v[176:179], v[104:107]
	v_mfma_f32_16x16x32_f16 v[104:107], v[164:167], v[172:175], v[104:107]
	v_mfma_f32_16x16x32_f16 v[112:115], v[164:167], v[180:183], v[112:115]
	v_mfma_f32_16x16x32_f16 v[112:115], v[168:171], v[184:187], v[112:115]
	v_mfma_f32_16x16x32_f16 v[108:111], v[160:163], v[184:187], v[108:111]
	v_mfma_f32_16x16x32_f16 v[108:111], v[156:159], v[180:183], v[108:111]
	v_mfma_f32_16x16x32_f16 v[116:119], v[156:159], v[188:191], v[116:119]
	v_mfma_f32_16x16x32_f16 v[116:119], v[160:163], v[192:195], v[116:119]
	v_mfma_f32_16x16x32_f16 v[120:123], v[168:171], v[192:195], v[120:123]
	v_mfma_f32_16x16x32_f16 v[120:123], v[164:167], v[188:191], v[120:123]
	v_mfma_f32_16x16x32_f16 v[128:131], v[164:167], v[196:199], v[128:131]
	v_mfma_f32_16x16x32_f16 v[128:131], v[168:171], v[200:203], v[128:131]
	s_setprio 2
	s_barrier
	v_mfma_f32_16x16x32_f16 v[124:127], v[160:163], v[200:203], v[124:127]
	v_mfma_f32_16x16x32_f16 v[124:127], v[156:159], v[196:199], v[124:127]
	s_setprio 0
	s_add_i32 s28, s28, 2
	s_add_u32 s8, s8, 0x100
	s_addc_u32 s9, s9, 0
	s_add_u32 s26, s26, 0x100
	s_addc_u32 s27, s27, 0
	s_cmp_gt_u32 s28, 29
	s_cbranch_scc0 .LBB0_532
	s_nop 0
	s_and_b64 vcc, exec, s[50:51]
	s_cbranch_vccz .LBB0_535
	s_barrier
